# wave-uniform slow-path test in the compressed pass, window pass and hipcc's selected-stream bodies: scalar s_and_b64 vcc,M,exec + s_cbranch_scc0 instead of v_cndmask 0/1 + v_cmp_ne + s_cbranch_vccz (9
# speedup vs baseline: 1.0028x; 1.0006x over previous
; #define NEG_INF (-__builtin_inff())
; DEV void ref_step(f32x4 (&s)[4], float& m, f32x4 (&O)[4], f32x4& L, ab8 (&pf)[2], bool colact) {
;     float mx = fmaxf(fmaxf(s[0][0], s[0][1]), fmaxf(s[0][2], s[0][3]));
; #pragma unroll
;     for (int kt = 1; kt < 4; ++kt) mx = fmaxf(mx, fmaxf(fmaxf(s[kt][0], s[kt][1]), fmaxf(s[kt][2], s[kt][3])));
;     const bool slow = (colact && m == NEG_INF) || mx > 64.f;
;     if (__any(slow)) {
;         mx = fmaxf(mx, __shfl_xor(mx, 16)); mx = fmaxf(mx, __shfl_xor(mx, 32));
;         const bool un = (m == NEG_INF);
;         const float d = (mx == NEG_INF) ? 0.f : (un ? mx : fmaxf(mx, 0.f));
;         const float sc = un ? 1.f : __builtin_amdgcn_exp2f(-d);
; #pragma unroll
;         for (int kt = 0; kt < 4; ++kt) s[kt] = s[kt] - d;
; #pragma unroll
;         for (int dt = 0; dt < 4; ++dt) O[dt] = O[dt] * sc;
;         L = L * sc;
;         m = un ? ((mx == NEG_INF) ? NEG_INF : mx) : m + d;
;     }
.LBB0_931:
	v_max_f32_e32 v21, v83, v83
	v_max_f32_e32 v113, v82, v82
	v_max_f32_e32 v21, v113, v21
	v_max_f32_e32 v113, v85, v85
	v_max_f32_e32 v114, v84, v84
	v_max_f32_e32 v113, v114, v113
	v_max_f32_e32 v114, v89, v89
	v_max_f32_e32 v115, v88, v88
	v_max_f32_e32 v114, v115, v114
	v_max3_f32 v114, v86, v87, v114
	v_max3_f32 v21, v21, v113, v114
	v_max_f32_e32 v113, v97, v97
	v_max_f32_e32 v114, v96, v96
	v_max_f32_e32 v113, v114, v113
	v_max_f32_e32 v114, v93, v93
	v_max_f32_e32 v115, v92, v92
	v_max_f32_e32 v114, v115, v114
	v_max3_f32 v113, v94, v95, v113
	v_max3_f32 v114, v90, v91, v114
	v_max3_f32 v21, v21, v113, v114
	v_cmp_lt_f32_e32 vcc, s96, v21
	s_or_b64 s[14:15], s[10:11], vcc
	s_and_b64 vcc, s[14:15], exec
	s_cbranch_scc0 .LBB0_933
	v_and_b32_e32 v114, 64, v139
	v_xor_b32_e32 v113, 16, v139
	v_add_u32_e32 v114, 64, v114
	v_cmp_lt_i32_e32 vcc, v113, v114
	s_nop 1
	v_cndmask_b32_e32 v113, v139, v113, vcc
	v_lshlrev_b32_e32 v113, 2, v113
	ds_bpermute_b32 v113, v113, v21
	v_max_f32_e32 v21, v21, v21
	s_waitcnt lgkmcnt(0)
	v_max_f32_e32 v113, v113, v113
	v_max_f32_e32 v21, v21, v113
	v_xor_b32_e32 v113, 32, v139
	v_cmp_lt_i32_e32 vcc, v113, v114
	s_nop 1
	v_cndmask_b32_e32 v113, v139, v113, vcc
	v_lshlrev_b32_e32 v113, 2, v113
	ds_bpermute_b32 v113, v113, v21
	s_waitcnt lgkmcnt(0)
	v_max_f32_e32 v113, v113, v113
	v_max_f32_e32 v21, v21, v113
	v_max_f32_e32 v113, 0, v21
	v_cndmask_b32_e64 v113, v113, v21, s[10:11]
	v_cmp_neq_f32_e32 vcc, s3, v21
	s_nop 1
	v_cndmask_b32_e32 v113, 0, v113, vcc
	v_exp_f32_e64 v114, -v113
	v_add_f32_e32 v109, v109, v113
	v_sub_f32_e32 v82, v82, v113
	v_sub_f32_e32 v83, v83, v113
	v_cndmask_b32_e64 v114, v114, 1.0, s[10:11]
	v_sub_f32_e32 v84, v84, v113
	v_sub_f32_e32 v85, v85, v113
	v_sub_f32_e32 v86, v86, v113
	v_sub_f32_e32 v87, v87, v113
	v_sub_f32_e32 v88, v88, v113
	v_sub_f32_e32 v89, v89, v113
	v_sub_f32_e32 v94, v94, v113
	v_sub_f32_e32 v95, v95, v113
	v_sub_f32_e32 v96, v96, v113
	v_sub_f32_e32 v97, v97, v113
	v_sub_f32_e32 v90, v90, v113
	v_sub_f32_e32 v91, v91, v113
	v_sub_f32_e32 v92, v92, v113
	v_sub_f32_e32 v93, v93, v113
	v_pk_mul_f32 v[56:57], v[56:57], v[114:115] op_sel_hi:[1,0]
	v_pk_mul_f32 v[54:55], v[54:55], v[114:115] op_sel_hi:[1,0]
	v_pk_mul_f32 v[48:49], v[48:49], v[114:115] op_sel_hi:[1,0]
	v_pk_mul_f32 v[46:47], v[46:47], v[114:115] op_sel_hi:[1,0]
	v_pk_mul_f32 v[44:45], v[44:45], v[114:115] op_sel_hi:[1,0]
	v_pk_mul_f32 v[42:43], v[42:43], v[114:115] op_sel_hi:[1,0]
	v_pk_mul_f32 v[52:53], v[52:53], v[114:115] op_sel_hi:[1,0]
	v_pk_mul_f32 v[50:51], v[50:51], v[114:115] op_sel_hi:[1,0]
	v_pk_mul_f32 v[64:65], v[64:65], v[114:115] op_sel_hi:[1,0]
	v_pk_mul_f32 v[62:63], v[62:63], v[114:115] op_sel_hi:[1,0]
	v_cndmask_b32_e64 v109, v109, v21, s[10:11]

; #define NEG_INF (-__builtin_inff())
; DEV void ref_step(f32x4 (&s)[4], float& m, f32x4 (&O)[4], f32x4& L, ab8 (&pf)[2], bool colact) {
;     float mx = fmaxf(fmaxf(s[0][0], s[0][1]), fmaxf(s[0][2], s[0][3]));
; #pragma unroll
;     for (int kt = 1; kt < 4; ++kt) mx = fmaxf(mx, fmaxf(fmaxf(s[kt][0], s[kt][1]), fmaxf(s[kt][2], s[kt][3])));
;     const bool slow = (colact && m == NEG_INF) || mx > 64.f;
;     if (__any(slow)) {
;         mx = fmaxf(mx, __shfl_xor(mx, 16)); mx = fmaxf(mx, __shfl_xor(mx, 32));
;         const bool un = (m == NEG_INF);
;         const float d = (mx == NEG_INF) ? 0.f : (un ? mx : fmaxf(mx, 0.f));
;         const float sc = un ? 1.f : __builtin_amdgcn_exp2f(-d);
; #pragma unroll
;         for (int kt = 0; kt < 4; ++kt) s[kt] = s[kt] - d;
; #pragma unroll
;         for (int dt = 0; dt < 4; ++dt) O[dt] = O[dt] * sc;
;         L = L * sc;
;         m = un ? ((mx == NEG_INF) ? NEG_INF : mx) : m + d;
;     }
.LBB0_937:
	v_max_f32_e32 v18, v71, v71
	v_max_f32_e32 v21, v70, v70
	v_max_f32_e32 v18, v21, v18
	v_max_f32_e32 v21, v73, v73
	v_max_f32_e32 v113, v72, v72
	v_max_f32_e32 v21, v113, v21
	v_max_f32_e32 v113, v77, v77
	v_max_f32_e32 v114, v76, v76
	v_max_f32_e32 v113, v114, v113
	v_max3_f32 v113, v74, v75, v113
	v_max3_f32 v18, v18, v21, v113
	v_max_f32_e32 v21, v81, v81
	v_max_f32_e32 v113, v80, v80
	v_max_f32_e32 v21, v113, v21
	v_max_f32_e32 v113, v69, v69
	v_max_f32_e32 v114, v68, v68
	v_max_f32_e32 v113, v114, v113
	v_max3_f32 v21, v78, v79, v21
	v_max3_f32 v113, v66, v67, v113
	v_max3_f32 v18, v18, v21, v113
	v_cmp_lt_f32_e32 vcc, s96, v18
	s_or_b64 s[10:11], s[8:9], vcc
	s_and_b64 vcc, s[10:11], exec
	s_cbranch_scc0 .LBB0_920
	v_and_b32_e32 v113, 64, v139
	v_xor_b32_e32 v21, 16, v139
	v_add_u32_e32 v113, 64, v113
	v_cmp_lt_i32_e32 vcc, v21, v113
	s_nop 1
	v_cndmask_b32_e32 v21, v139, v21, vcc
	v_lshlrev_b32_e32 v21, 2, v21
	ds_bpermute_b32 v21, v21, v18
	v_max_f32_e32 v18, v18, v18
	s_waitcnt lgkmcnt(0)
	v_max_f32_e32 v21, v21, v21
	v_max_f32_e32 v18, v18, v21
	v_xor_b32_e32 v21, 32, v139
	v_cmp_lt_i32_e32 vcc, v21, v113
	s_nop 1
	v_cndmask_b32_e32 v21, v139, v21, vcc
	v_lshlrev_b32_e32 v21, 2, v21
	ds_bpermute_b32 v21, v21, v18
	s_waitcnt lgkmcnt(0)
	v_max_f32_e32 v21, v21, v21
	v_max_f32_e32 v21, v18, v21
	v_max_f32_e32 v18, 0, v21
	v_cndmask_b32_e64 v18, v18, v21, s[8:9]
	v_cmp_neq_f32_e32 vcc, s3, v21
	s_nop 1
	v_cndmask_b32_e32 v113, 0, v18, vcc
	v_exp_f32_e64 v18, -v113
	v_sub_f32_e32 v70, v70, v113
	v_sub_f32_e32 v71, v71, v113
	v_sub_f32_e32 v72, v72, v113
	v_cndmask_b32_e64 v18, v18, 1.0, s[8:9]
	v_pk_mul_f32 v[40:41], v[40:41], v[18:19] op_sel_hi:[1,0]
	v_pk_mul_f32 v[38:39], v[38:39], v[18:19] op_sel_hi:[1,0]
	v_pk_mul_f32 v[32:33], v[32:33], v[18:19] op_sel_hi:[1,0]
	v_pk_mul_f32 v[30:31], v[30:31], v[18:19] op_sel_hi:[1,0]
	v_pk_mul_f32 v[28:29], v[28:29], v[18:19] op_sel_hi:[1,0]
	v_pk_mul_f32 v[26:27], v[26:27], v[18:19] op_sel_hi:[1,0]
	v_pk_mul_f32 v[36:37], v[36:37], v[18:19] op_sel_hi:[1,0]
	v_pk_mul_f32 v[34:35], v[34:35], v[18:19] op_sel_hi:[1,0]
	v_pk_mul_f32 v[60:61], v[60:61], v[18:19] op_sel_hi:[1,0]
	v_pk_mul_f32 v[58:59], v[58:59], v[18:19] op_sel_hi:[1,0]
	v_add_f32_e32 v18, v20, v113
	v_sub_f32_e32 v73, v73, v113
	v_sub_f32_e32 v74, v74, v113
	v_sub_f32_e32 v75, v75, v113
	v_sub_f32_e32 v76, v76, v113
	v_sub_f32_e32 v77, v77, v113
	v_sub_f32_e32 v78, v78, v113
	v_sub_f32_e32 v79, v79, v113
	v_sub_f32_e32 v80, v80, v113
	v_sub_f32_e32 v81, v81, v113
	v_sub_f32_e32 v66, v66, v113
	v_sub_f32_e32 v67, v67, v113
	v_sub_f32_e32 v68, v68, v113
	v_sub_f32_e32 v69, v69, v113
	v_cndmask_b32_e64 v20, v18, v21, s[8:9]
	s_branch .LBB0_920

; #define NEG_INF (-__builtin_inff())
; DEV void ref_step(f32x4 (&s)[4], float& m, f32x4 (&O)[4], f32x4& L, ab8 (&pf)[2], bool colact) {
;     float mx = fmaxf(fmaxf(s[0][0], s[0][1]), fmaxf(s[0][2], s[0][3]));
; #pragma unroll
;     for (int kt = 1; kt < 4; ++kt) mx = fmaxf(mx, fmaxf(fmaxf(s[kt][0], s[kt][1]), fmaxf(s[kt][2], s[kt][3])));
;     const bool slow = (colact && m == NEG_INF) || mx > 64.f;
;     if (__any(slow)) {
;         mx = fmaxf(mx, __shfl_xor(mx, 16)); mx = fmaxf(mx, __shfl_xor(mx, 32));
;         const bool un = (m == NEG_INF);
;         const float d = (mx == NEG_INF) ? 0.f : (un ? mx : fmaxf(mx, 0.f));
;         const float sc = un ? 1.f : __builtin_amdgcn_exp2f(-d);
; #pragma unroll
;         for (int kt = 0; kt < 4; ++kt) s[kt] = s[kt] - d;
; #pragma unroll
;         for (int dt = 0; dt < 4; ++dt) O[dt] = O[dt] * sc;
;         L = L * sc;
;         m = un ? ((mx == NEG_INF) ? NEG_INF : mx) : m + d;
;     }
.LBB0_1189:
	v_max_f32_e32 v98, v83, v83
	v_max_f32_e32 v99, v82, v82
	v_max_f32_e32 v98, v99, v98
	v_max_f32_e32 v99, v85, v85
	v_max_f32_e32 v100, v84, v84
	v_max_f32_e32 v99, v100, v99
	v_max_f32_e32 v100, v89, v89
	v_max_f32_e32 v101, v88, v88
	v_max_f32_e32 v100, v101, v100
	v_max3_f32 v100, v86, v87, v100
	v_max3_f32 v98, v98, v99, v100
	v_max_f32_e32 v99, v93, v93
	v_max_f32_e32 v100, v92, v92
	v_max_f32_e32 v99, v100, v99
	v_max_f32_e32 v100, v97, v97
	v_max_f32_e32 v101, v96, v96
	v_max_f32_e32 v100, v101, v100
	v_max3_f32 v99, v90, v91, v99
	v_max3_f32 v100, v94, v95, v100
	v_max3_f32 v98, v98, v99, v100
	s_and_b64 s[10:11], s[10:11], s[14:15]
	v_cmp_lt_f32_e32 vcc, s96, v98
	s_or_b64 s[10:11], s[10:11], vcc
	s_and_b64 vcc, s[10:11], exec
	s_cbranch_scc0 .LBB0_1253
	ds_bpermute_b32 v99, v210, v98
	v_max_f32_e32 v98, v98, v98
	s_waitcnt lgkmcnt(0)
	v_max_f32_e32 v99, v99, v99
	v_max_f32_e32 v98, v98, v99
	ds_bpermute_b32 v99, v211, v98
	s_waitcnt lgkmcnt(0)
	v_max_f32_e32 v99, v99, v99
	v_max_f32_e32 v99, v98, v99
	v_max_f32_e32 v98, 0, v99
	v_cndmask_b32_e64 v98, v98, v99, s[14:15]
	v_cmp_neq_f32_e32 vcc, s3, v99
	s_nop 1
	v_cndmask_b32_e32 v100, 0, v98, vcc
	v_exp_f32_e64 v98, -v100
	v_sub_f32_e32 v82, v82, v100
	v_sub_f32_e32 v83, v83, v100
	v_sub_f32_e32 v84, v84, v100
	v_cndmask_b32_e64 v98, v98, 1.0, s[14:15]
	v_pk_mul_f32 v[64:65], v[64:65], v[98:99] op_sel_hi:[1,0]
	v_pk_mul_f32 v[62:63], v[62:63], v[98:99] op_sel_hi:[1,0]
	v_pk_mul_f32 v[56:57], v[56:57], v[98:99] op_sel_hi:[1,0]
	v_pk_mul_f32 v[54:55], v[54:55], v[98:99] op_sel_hi:[1,0]
	v_pk_mul_f32 v[52:53], v[52:53], v[98:99] op_sel_hi:[1,0]
	v_pk_mul_f32 v[50:51], v[50:51], v[98:99] op_sel_hi:[1,0]
	v_pk_mul_f32 v[48:49], v[48:49], v[98:99] op_sel_hi:[1,0]
	v_pk_mul_f32 v[46:47], v[46:47], v[98:99] op_sel_hi:[1,0]
	v_pk_mul_f32 v[60:61], v[60:61], v[98:99] op_sel_hi:[1,0]
	v_pk_mul_f32 v[58:59], v[58:59], v[98:99] op_sel_hi:[1,0]
	v_add_f32_e32 v98, v213, v100
	v_sub_f32_e32 v85, v85, v100
	v_sub_f32_e32 v86, v86, v100
	v_sub_f32_e32 v87, v87, v100
	v_sub_f32_e32 v88, v88, v100
	v_sub_f32_e32 v89, v89, v100
	v_sub_f32_e32 v90, v90, v100
	v_sub_f32_e32 v91, v91, v100
	v_sub_f32_e32 v92, v92, v100
	v_sub_f32_e32 v93, v93, v100
	v_sub_f32_e32 v94, v94, v100
	v_sub_f32_e32 v95, v95, v100
	v_sub_f32_e32 v96, v96, v100
	v_sub_f32_e32 v97, v97, v100
	v_cndmask_b32_e64 v215, v98, v99, s[14:15]
	s_and_b64 vcc, exec, s[16:17]
	s_cbranch_vccnz .LBB0_1192

; #define NEG_INF (-__builtin_inff())
; DEV void ref_step(f32x4 (&s)[4], float& m, f32x4 (&O)[4], f32x4& L, ab8 (&pf)[2], bool colact) {
;     float mx = fmaxf(fmaxf(s[0][0], s[0][1]), fmaxf(s[0][2], s[0][3]));
; #pragma unroll
;     for (int kt = 1; kt < 4; ++kt) mx = fmaxf(mx, fmaxf(fmaxf(s[kt][0], s[kt][1]), fmaxf(s[kt][2], s[kt][3])));
;     const bool slow = (colact && m == NEG_INF) || mx > 64.f;
;     if (__any(slow)) {
;         mx = fmaxf(mx, __shfl_xor(mx, 16)); mx = fmaxf(mx, __shfl_xor(mx, 32));
;         const bool un = (m == NEG_INF);
;         const float d = (mx == NEG_INF) ? 0.f : (un ? mx : fmaxf(mx, 0.f));
;         const float sc = un ? 1.f : __builtin_amdgcn_exp2f(-d);
; #pragma unroll
;         for (int kt = 0; kt < 4; ++kt) s[kt] = s[kt] - d;
; #pragma unroll
;         for (int dt = 0; dt < 4; ++dt) O[dt] = O[dt] * sc;
;         L = L * sc;
;         m = un ? ((mx == NEG_INF) ? NEG_INF : mx) : m + d;
;     }
.LBB0_1192:
	v_max_f32_e32 v98, v67, v67
	v_max_f32_e32 v99, v66, v66
	v_max_f32_e32 v98, v99, v98
	v_max_f32_e32 v99, v69, v69
	v_max_f32_e32 v100, v68, v68
	v_max_f32_e32 v99, v100, v99
	v_max_f32_e32 v100, v73, v73
	v_max_f32_e32 v101, v72, v72
	v_max_f32_e32 v100, v101, v100
	v_max3_f32 v100, v70, v71, v100
	v_max3_f32 v98, v98, v99, v100
	v_max_f32_e32 v99, v77, v77
	v_max_f32_e32 v100, v76, v76
	v_max_f32_e32 v99, v100, v99
	v_max_f32_e32 v100, v81, v81
	v_max_f32_e32 v101, v80, v80
	v_max_f32_e32 v100, v101, v100
	v_max3_f32 v99, v74, v75, v99
	v_max3_f32 v100, v78, v79, v100
	v_max3_f32 v98, v98, v99, v100
	s_and_b64 s[8:9], s[8:9], s[12:13]
	v_cmp_lt_f32_e32 vcc, s96, v98
	s_or_b64 s[8:9], s[8:9], vcc
	s_and_b64 vcc, s[8:9], exec
	s_cbranch_scc0 .LBB0_1194
	ds_bpermute_b32 v99, v210, v98
	v_max_f32_e32 v98, v98, v98
	s_waitcnt lgkmcnt(0)
	v_max_f32_e32 v99, v99, v99
	v_max_f32_e32 v98, v98, v99
	ds_bpermute_b32 v99, v211, v98
	s_waitcnt lgkmcnt(0)
	v_max_f32_e32 v99, v99, v99
	v_max_f32_e32 v99, v98, v99
	v_max_f32_e32 v98, 0, v99
	v_cndmask_b32_e64 v98, v98, v99, s[12:13]
	v_cmp_neq_f32_e32 vcc, s3, v99
	s_nop 1
	v_cndmask_b32_e32 v100, 0, v98, vcc
	v_exp_f32_e64 v98, -v100
	v_sub_f32_e32 v66, v66, v100
	v_sub_f32_e32 v67, v67, v100
	v_sub_f32_e32 v68, v68, v100
	v_cndmask_b32_e64 v98, v98, 1.0, s[12:13]
	v_pk_mul_f32 v[40:41], v[40:41], v[98:99] op_sel_hi:[1,0]
	v_pk_mul_f32 v[38:39], v[38:39], v[98:99] op_sel_hi:[1,0]
	v_pk_mul_f32 v[36:37], v[36:37], v[98:99] op_sel_hi:[1,0]
	v_pk_mul_f32 v[34:35], v[34:35], v[98:99] op_sel_hi:[1,0]
	v_pk_mul_f32 v[32:33], v[32:33], v[98:99] op_sel_hi:[1,0]
	v_pk_mul_f32 v[30:31], v[30:31], v[98:99] op_sel_hi:[1,0]
	v_pk_mul_f32 v[28:29], v[28:29], v[98:99] op_sel_hi:[1,0]
	v_pk_mul_f32 v[26:27], v[26:27], v[98:99] op_sel_hi:[1,0]
	v_pk_mul_f32 v[44:45], v[44:45], v[98:99] op_sel_hi:[1,0]
	v_pk_mul_f32 v[42:43], v[42:43], v[98:99] op_sel_hi:[1,0]
	v_add_f32_e32 v98, v212, v100
	v_sub_f32_e32 v69, v69, v100
	v_sub_f32_e32 v70, v70, v100
	v_sub_f32_e32 v71, v71, v100
	v_sub_f32_e32 v72, v72, v100
	v_sub_f32_e32 v73, v73, v100
	v_sub_f32_e32 v74, v74, v100
	v_sub_f32_e32 v75, v75, v100
	v_sub_f32_e32 v76, v76, v100
	v_sub_f32_e32 v77, v77, v100
	v_sub_f32_e32 v78, v78, v100
	v_sub_f32_e32 v79, v79, v100
	v_sub_f32_e32 v80, v80, v100
	v_sub_f32_e32 v81, v81, v100
	v_cndmask_b32_e64 v212, v98, v99, s[12:13]

; #define NEG_INF (-__builtin_inff())
; DEV void ref_step(f32x4 (&s)[4], float& m, f32x4 (&O)[4], f32x4& L, ab8 (&pf)[2], bool colact) {
;     float mx = fmaxf(fmaxf(s[0][0], s[0][1]), fmaxf(s[0][2], s[0][3]));
; #pragma unroll
;     for (int kt = 1; kt < 4; ++kt) mx = fmaxf(mx, fmaxf(fmaxf(s[kt][0], s[kt][1]), fmaxf(s[kt][2], s[kt][3])));
;     const bool slow = (colact && m == NEG_INF) || mx > 64.f;
;     if (__any(slow)) {
;         mx = fmaxf(mx, __shfl_xor(mx, 16)); mx = fmaxf(mx, __shfl_xor(mx, 32));
;         const bool un = (m == NEG_INF);
;         const float d = (mx == NEG_INF) ? 0.f : (un ? mx : fmaxf(mx, 0.f));
;         const float sc = un ? 1.f : __builtin_amdgcn_exp2f(-d);
; #pragma unroll
;         for (int kt = 0; kt < 4; ++kt) s[kt] = s[kt] - d;
; #pragma unroll
;         for (int dt = 0; dt < 4; ++dt) O[dt] = O[dt] * sc;
;         L = L * sc;
;         m = un ? ((mx == NEG_INF) ? NEG_INF : mx) : m + d;
;     }
.LBB0_1241:
	v_max_f32_e32 v98, v83, v83
	v_max_f32_e32 v99, v82, v82
	v_max_f32_e32 v98, v99, v98
	v_max_f32_e32 v99, v85, v85
	v_max_f32_e32 v100, v84, v84
	v_max_f32_e32 v99, v100, v99
	v_max_f32_e32 v100, v89, v89
	v_max_f32_e32 v101, v88, v88
	v_max_f32_e32 v100, v101, v100
	v_max3_f32 v100, v86, v87, v100
	v_max3_f32 v98, v98, v99, v100
	v_max_f32_e32 v99, v93, v93
	v_max_f32_e32 v100, v92, v92
	v_max_f32_e32 v99, v100, v99
	v_max_f32_e32 v100, v97, v97
	v_max_f32_e32 v101, v96, v96
	v_max_f32_e32 v100, v101, v100
	v_max3_f32 v99, v90, v91, v99
	v_max3_f32 v100, v94, v95, v100
	v_max3_f32 v98, v98, v99, v100
	s_and_b64 s[10:11], s[10:11], s[14:15]
	v_cmp_lt_f32_e32 vcc, s96, v98
	s_or_b64 s[10:11], s[10:11], vcc
	s_and_b64 vcc, s[10:11], exec
	s_cbranch_scc0 .LBB0_1255
	ds_bpermute_b32 v99, v210, v98
	v_max_f32_e32 v98, v98, v98
	s_waitcnt lgkmcnt(0)
	v_max_f32_e32 v99, v99, v99
	v_max_f32_e32 v98, v98, v99
	ds_bpermute_b32 v99, v211, v98
	s_waitcnt lgkmcnt(0)
	v_max_f32_e32 v99, v99, v99
	v_max_f32_e32 v99, v98, v99
	v_max_f32_e32 v98, 0, v99
	v_cndmask_b32_e64 v98, v98, v99, s[14:15]
	v_cmp_neq_f32_e32 vcc, s3, v99
	s_nop 1
	v_cndmask_b32_e32 v100, 0, v98, vcc
	v_exp_f32_e64 v98, -v100
	v_sub_f32_e32 v82, v82, v100
	v_sub_f32_e32 v83, v83, v100
	v_sub_f32_e32 v84, v84, v100
	v_cndmask_b32_e64 v98, v98, 1.0, s[14:15]
	v_pk_mul_f32 v[64:65], v[64:65], v[98:99] op_sel_hi:[1,0]
	v_pk_mul_f32 v[62:63], v[62:63], v[98:99] op_sel_hi:[1,0]
	v_pk_mul_f32 v[56:57], v[56:57], v[98:99] op_sel_hi:[1,0]
	v_pk_mul_f32 v[54:55], v[54:55], v[98:99] op_sel_hi:[1,0]
	v_pk_mul_f32 v[52:53], v[52:53], v[98:99] op_sel_hi:[1,0]
	v_pk_mul_f32 v[50:51], v[50:51], v[98:99] op_sel_hi:[1,0]
	v_pk_mul_f32 v[48:49], v[48:49], v[98:99] op_sel_hi:[1,0]
	v_pk_mul_f32 v[46:47], v[46:47], v[98:99] op_sel_hi:[1,0]
	v_pk_mul_f32 v[60:61], v[60:61], v[98:99] op_sel_hi:[1,0]
	v_pk_mul_f32 v[58:59], v[58:59], v[98:99] op_sel_hi:[1,0]
	v_add_f32_e32 v98, v213, v100
	v_sub_f32_e32 v85, v85, v100
	v_sub_f32_e32 v86, v86, v100
	v_sub_f32_e32 v87, v87, v100
	v_sub_f32_e32 v88, v88, v100
	v_sub_f32_e32 v89, v89, v100
	v_sub_f32_e32 v90, v90, v100
	v_sub_f32_e32 v91, v91, v100
	v_sub_f32_e32 v92, v92, v100
	v_sub_f32_e32 v93, v93, v100
	v_sub_f32_e32 v94, v94, v100
	v_sub_f32_e32 v95, v95, v100
	v_sub_f32_e32 v96, v96, v100
	v_sub_f32_e32 v97, v97, v100
	v_cndmask_b32_e64 v217, v98, v99, s[14:15]
	s_and_b64 vcc, exec, s[16:17]
	s_cbranch_vccnz .LBB0_1244

; #define NEG_INF (-__builtin_inff())
; DEV void ref_step(f32x4 (&s)[4], float& m, f32x4 (&O)[4], f32x4& L, ab8 (&pf)[2], bool colact) {
;     float mx = fmaxf(fmaxf(s[0][0], s[0][1]), fmaxf(s[0][2], s[0][3]));
; #pragma unroll
;     for (int kt = 1; kt < 4; ++kt) mx = fmaxf(mx, fmaxf(fmaxf(s[kt][0], s[kt][1]), fmaxf(s[kt][2], s[kt][3])));
;     const bool slow = (colact && m == NEG_INF) || mx > 64.f;
;     if (__any(slow)) {
;         mx = fmaxf(mx, __shfl_xor(mx, 16)); mx = fmaxf(mx, __shfl_xor(mx, 32));
;         const bool un = (m == NEG_INF);
;         const float d = (mx == NEG_INF) ? 0.f : (un ? mx : fmaxf(mx, 0.f));
;         const float sc = un ? 1.f : __builtin_amdgcn_exp2f(-d);
; #pragma unroll
;         for (int kt = 0; kt < 4; ++kt) s[kt] = s[kt] - d;
; #pragma unroll
;         for (int dt = 0; dt < 4; ++dt) O[dt] = O[dt] * sc;
;         L = L * sc;
;         m = un ? ((mx == NEG_INF) ? NEG_INF : mx) : m + d;
;     }
; DEV void attn_unit_mfma(Frame& F, int qg, int kv) {
;     ...
;         const int it = i + iw0, p0 = t0 - 512 + 64 * it; const bool near = it >= 6; const float bi = near ? 0.f : C.b31;
;         f32x4 s[2][4]; qk64(Kb, C, qf, s, cinit(bi, m[0], true), cinit(bi, m[1], true), true, true);
;         ab8 pf[2][2], vf[4][2]; pv_load(Vb, C, vf); __builtin_amdgcn_sched_barrier(0);
; #pragma unroll
;         for (int g = 0; g < 2; ++g) { if (near) mask_bias<true, false>(s[g], C, C.tq[g], p0, 1, true); else if (it == 0) mask_bias<false, true>(s[g], C, C.tq[g], p0, 1, true);
;             ref_step(s[g], m[g], O[g], L[g], pf[g], true); }
.LBB0_1297:
	v_max_f32_e32 v98, v115, v115
	v_max_f32_e32 v99, v114, v114
	v_max_f32_e32 v98, v99, v98
	v_max_f32_e32 v99, v117, v117
	v_max_f32_e32 v100, v116, v116
	v_max_f32_e32 v99, v100, v99
	v_max_f32_e32 v100, v119, v119
	v_max_f32_e32 v101, v118, v118
	v_max_f32_e32 v100, v101, v100
	v_max3_f32 v100, v120, v121, v100
	v_max3_f32 v98, v98, v99, v100
	v_max_f32_e32 v99, v127, v127
	v_max_f32_e32 v100, v126, v126
	v_max_f32_e32 v99, v100, v99
	v_max_f32_e32 v100, v123, v123
	v_max_f32_e32 v101, v122, v122
	v_max_f32_e32 v100, v101, v100
	v_max3_f32 v99, v124, v125, v99
	v_max3_f32 v100, v128, v129, v100
	v_max3_f32 v98, v98, v99, v100
	v_cmp_lt_f32_e32 vcc, s96, v98
	s_or_b64 s[26:27], s[24:25], vcc
	s_and_b64 vcc, s[26:27], exec
	s_cbranch_scc0 .LBB0_1265
	ds_bpermute_b32 v99, v1, v98
	v_max_f32_e32 v98, v98, v98
	s_waitcnt lgkmcnt(0)
	v_max_f32_e32 v99, v99, v99
	v_max_f32_e32 v98, v98, v99
	ds_bpermute_b32 v99, v132, v98
	s_waitcnt lgkmcnt(0)
	v_max_f32_e32 v99, v99, v99
	v_max_f32_e32 v99, v98, v99
	v_max_f32_e32 v98, 0, v99
	v_cndmask_b32_e64 v98, v98, v99, s[24:25]
	v_cmp_neq_f32_e32 vcc, s3, v99
	s_nop 1
	v_cndmask_b32_e32 v100, 0, v98, vcc
	v_exp_f32_e64 v98, -v100
	v_sub_f32_e32 v114, v114, v100
	v_sub_f32_e32 v115, v115, v100
	v_sub_f32_e32 v116, v116, v100
	v_cndmask_b32_e64 v98, v98, 1.0, s[24:25]
	v_pk_mul_f32 v[40:41], v[40:41], v[98:99] op_sel_hi:[1,0]
	v_pk_mul_f32 v[38:39], v[38:39], v[98:99] op_sel_hi:[1,0]
	v_pk_mul_f32 v[36:37], v[36:37], v[98:99] op_sel_hi:[1,0]
	v_pk_mul_f32 v[34:35], v[34:35], v[98:99] op_sel_hi:[1,0]
	v_pk_mul_f32 v[32:33], v[32:33], v[98:99] op_sel_hi:[1,0]
	v_pk_mul_f32 v[30:31], v[30:31], v[98:99] op_sel_hi:[1,0]
	v_pk_mul_f32 v[28:29], v[28:29], v[98:99] op_sel_hi:[1,0]
	v_pk_mul_f32 v[26:27], v[26:27], v[98:99] op_sel_hi:[1,0]
	v_pk_mul_f32 v[44:45], v[44:45], v[98:99] op_sel_hi:[1,0]
	v_pk_mul_f32 v[42:43], v[42:43], v[98:99] op_sel_hi:[1,0]
	v_add_f32_e32 v98, v135, v100
	v_sub_f32_e32 v117, v117, v100
	v_sub_f32_e32 v120, v120, v100
	v_sub_f32_e32 v121, v121, v100
	v_sub_f32_e32 v118, v118, v100
	v_sub_f32_e32 v119, v119, v100
	v_sub_f32_e32 v124, v124, v100
	v_sub_f32_e32 v125, v125, v100
	v_sub_f32_e32 v126, v126, v100
	v_sub_f32_e32 v127, v127, v100
	v_sub_f32_e32 v128, v128, v100
	v_sub_f32_e32 v129, v129, v100
	v_sub_f32_e32 v122, v122, v100
	v_sub_f32_e32 v123, v123, v100
	v_cndmask_b32_e64 v135, v98, v99, s[24:25]
	s_branch .LBB0_1265
